# v60 + inproj1 k-loop: LDS-DMA lane offsets and tile bases precomputed (saddr form), so the eight loads of a k-step issue back to back right after the barrier
# speedup vs baseline: 1.0034x; 1.0034x over previous
.LBB0_568:
	s_ashr_i32 s1, s0, 31
	s_lshl_b64 s[6:7], s[0:1], 18
	s_ashr_i32 s5, s4, 31
	v_readfirstlane_b32 s1, v74
	v_add_u32_e32 v4, 0x4000, v74
	s_lshl_b64 s[14:15], s[4:5], 18
	v_lshl_add_u64 v[0:1], v[64:65], 0, s[6:7]
	s_mov_b32 m0, s1
	v_readfirstlane_b32 s1, v4
	v_add_u32_e32 v6, 0x1000, v74
	v_lshl_add_u64 v[2:3], v[66:67], 0, s[14:15]
	global_load_lds_dwordx4 v[0:1], off
	s_mov_b32 m0, s1
	s_mov_b64 s[34:35], 0x10000
	v_readfirstlane_b32 s1, v6
	v_add_u32_e32 v6, 0x5000, v74
	global_load_lds_dwordx4 v[2:3], off
	v_lshl_add_u64 v[4:5], v[0:1], 0, s[34:35]
	s_mov_b32 m0, s1
	v_readfirstlane_b32 s1, v6
	v_add_u32_e32 v6, 0x2000, v74
	global_load_lds_dwordx4 v[4:5], off
	v_lshl_add_u64 v[4:5], v[2:3], 0, s[34:35]
	s_mov_b32 m0, s1
	s_mov_b64 s[34:35], 0x20000
	v_readfirstlane_b32 s1, v6
	v_add_u32_e32 v6, 0x6000, v74
	global_load_lds_dwordx4 v[4:5], off
	v_lshl_add_u64 v[4:5], v[0:1], 0, s[34:35]
	s_mov_b32 m0, s1
	v_readfirstlane_b32 s1, v6
	global_load_lds_dwordx4 v[4:5], off
	v_lshl_add_u64 v[4:5], v[2:3], 0, s[34:35]
	s_mov_b32 m0, s1
	s_mov_b64 s[34:35], 0x30000
	global_load_lds_dwordx4 v[4:5], off
	v_add_u32_e32 v4, 0x3000, v74
	v_lshl_add_u64 v[0:1], v[0:1], 0, s[34:35]
	v_readfirstlane_b32 s1, v4
	s_mov_b32 m0, s1
	v_lshl_add_u64 v[70:71], v[68:69], 0, s[6:7]
	global_load_lds_dwordx4 v[0:1], off
	v_lshl_add_u64 v[0:1], v[2:3], 0, s[34:35]
	v_add_u32_e32 v2, 0x7000, v74
	v_lshl_add_u64 v[72:73], v[68:69], 0, s[14:15]
	v_readfirstlane_b32 s1, v2
	s_mov_b32 m0, s1
	s_mov_b32 s1, 0
	global_load_lds_dwordx4 v[0:1], off
	s_waitcnt vmcnt(0)
	v_mov_b32_e32 v0, 0
	s_mov_b64 s[6:7], 0
	v_mov_b32_e32 v1, v0
	v_mov_b32_e32 v2, v0
	v_mov_b32_e32 v3, v0
	v_mov_b32_e32 v4, v0
	v_mov_b32_e32 v5, v0
	v_mov_b32_e32 v6, v0
	v_mov_b32_e32 v7, v0
	v_mov_b32_e32 v8, v0
	v_mov_b32_e32 v9, v0
	v_mov_b32_e32 v10, v0
	v_mov_b32_e32 v11, v0
	v_mov_b32_e32 v12, v0
	v_mov_b32_e32 v13, v0
	v_mov_b32_e32 v14, v0
	v_mov_b32_e32 v15, v0
	v_mov_b32_e32 v16, v0
	v_mov_b32_e32 v17, v0
	v_mov_b32_e32 v18, v0
	v_mov_b32_e32 v19, v0
	v_mov_b32_e32 v20, v0
	v_mov_b32_e32 v21, v0
	v_mov_b32_e32 v22, v0
	v_mov_b32_e32 v23, v0
	v_mov_b32_e32 v24, v0
	v_mov_b32_e32 v25, v0
	v_mov_b32_e32 v26, v0
	v_mov_b32_e32 v27, v0
	v_mov_b32_e32 v28, v0
	v_mov_b32_e32 v29, v0
	v_mov_b32_e32 v30, v0
	v_mov_b32_e32 v31, v0
	v_mov_b32_e32 v32, v0
	v_mov_b32_e32 v33, v0
	v_mov_b32_e32 v34, v0
	v_mov_b32_e32 v35, v0
	v_mov_b32_e32 v36, v0
	v_mov_b32_e32 v37, v0
	v_mov_b32_e32 v38, v0
	v_mov_b32_e32 v39, v0
	v_mov_b32_e32 v40, v0
	v_mov_b32_e32 v41, v0
	v_mov_b32_e32 v42, v0
	v_mov_b32_e32 v43, v0
	v_mov_b32_e32 v44, v0
	v_mov_b32_e32 v45, v0
	v_mov_b32_e32 v46, v0
	v_mov_b32_e32 v47, v0
	v_mov_b32_e32 v48, v0
	v_mov_b32_e32 v49, v0
	v_mov_b32_e32 v50, v0
	v_mov_b32_e32 v51, v0
	v_mov_b32_e32 v52, v0
	v_mov_b32_e32 v53, v0
	v_mov_b32_e32 v54, v0
	v_mov_b32_e32 v55, v0
	v_mov_b32_e32 v56, v0
	v_mov_b32_e32 v57, v0
	v_mov_b32_e32 v58, v0
	v_mov_b32_e32 v59, v0
	v_mov_b32_e32 v60, v0
	v_mov_b32_e32 v61, v0
	v_mov_b32_e32 v62, v0
	v_mov_b32_e32 v63, v0
	s_mov_b64 s[34:35], 0x4101080
	s_mov_b64 s[36:37], 0x4111080
	s_mov_b64 s[38:39], 0x4121080
	s_mov_b64 s[40:41], 0x4131080
	v_readlane_b32 s34, v254, 11
	v_readlane_b32 s35, v254, 12
	s_add_u32 s36, s34, 0x12cb1080
	s_addc_u32 s37, s35, 0
	s_add_u32 s34, s34, 0x4101080
	s_addc_u32 s35, s35, 0
	s_ashr_i32 s1, s0, 31
	s_lshl_b64 s[38:39], s[0:1], 18
	s_add_u32 s34, s34, s38
	s_addc_u32 s35, s35, s39
	s_ashr_i32 s5, s4, 31
	s_lshl_b64 s[38:39], s[4:5], 18
	s_add_u32 s36, s36, s38
	s_addc_u32 s37, s37, s39
	v_lshrrev_b32_e32 v242, 3, v176
	v_and_b32_e32 v243, 7, v176
	v_bfe_u32 v244, v176, 4, 3
	v_xor_b32_e32 v243, v243, v244
	v_lshlrev_b32_e32 v243, 4, v243
	v_lshl_add_u32 v242, v242, 11, v243
	v_add_u32_e32 v243, 0x10000, v242
	v_add_u32_e32 v244, 0x20000, v242
	v_add_u32_e32 v245, 0x30000, v242
	v_readfirstlane_b32 s38, v74
	s_mov_b32 s1, 0
	s_waitcnt vmcnt(0) lgkmcnt(0)
	s_barrier
.LBB0_569:
	s_add_i32 s5, s1, 0x8000
	s_and_b32 s13, s5, 0x8000
	s_add_u32 s13, s13, s38
	s_and_b32 s1, s1, 0x8000
	s_add_i32 s1, s1, 0
	v_add_u32_e32 v81, s1, v75
	v_add_u32_e32 v94, v81, v76
	v_add_u32_e32 v81, v81, v77
	s_add_u32 m0, s13, 0
	ds_read_b128 v[82:85], v94
	global_load_lds_dwordx4 v242, s[34:35]
	ds_read_b128 v[86:89], v94 offset:2048
	s_add_u32 m0, s13, 4096
	ds_read_b128 v[90:93], v94 offset:4096
	global_load_lds_dwordx4 v243, s[34:35]
	ds_read_b128 v[100:103], v94 offset:6144
	s_add_u32 m0, s13, 8192
	ds_read_b128 v[104:107], v81 offset:16384
	global_load_lds_dwordx4 v244, s[34:35]
	ds_read_b128 v[108:111], v81 offset:18432
	s_add_u32 m0, s13, 12288
	ds_read_b128 v[112:115], v81 offset:20480
	global_load_lds_dwordx4 v245, s[34:35]
	ds_read_b128 v[116:119], v81 offset:22528
	v_add_u32_e32 v206, s1, v78
	v_add_u32_e32 v207, v206, v76
	v_add_u32_e32 v208, v206, v77
	s_add_u32 m0, s13, 16384
	ds_read_b128 v[210:213], v207
	global_load_lds_dwordx4 v242, s[36:37]
	ds_read_b128 v[214:217], v207 offset:2048
	s_add_u32 m0, s13, 20480
	ds_read_b128 v[218:221], v207 offset:4096
	global_load_lds_dwordx4 v243, s[36:37]
	ds_read_b128 v[222:225], v207 offset:6144
	s_add_u32 m0, s13, 24576
	ds_read_b128 v[226:229], v208 offset:16384
	global_load_lds_dwordx4 v244, s[36:37]
	ds_read_b128 v[230:233], v208 offset:18432
	s_add_u32 m0, s13, 28672
	ds_read_b128 v[234:237], v208 offset:20480
	global_load_lds_dwordx4 v245, s[36:37]
	ds_read_b128 v[238:241], v208 offset:22528
	s_add_u32 s34, s34, 0x80
	s_addc_u32 s35, s35, 0
	s_add_u32 s36, s36, 0x80
	s_addc_u32 s37, s37, 0
	s_setprio 1
	s_waitcnt lgkmcnt(8)
	v_mfma_f32_16x16x32_bf16 v[60:63], v[104:107], v[82:85], v[60:63]
	v_mfma_f32_16x16x32_bf16 v[56:59], v[108:111], v[82:85], v[56:59]
	v_mfma_f32_16x16x32_bf16 v[52:55], v[112:115], v[82:85], v[52:55]
	v_mfma_f32_16x16x32_bf16 v[48:51], v[116:119], v[82:85], v[48:51]
	v_mfma_f32_16x16x32_bf16 v[44:47], v[104:107], v[86:89], v[44:47]
	v_mfma_f32_16x16x32_bf16 v[40:43], v[108:111], v[86:89], v[40:43]
	v_mfma_f32_16x16x32_bf16 v[36:39], v[112:115], v[86:89], v[36:39]
	v_mfma_f32_16x16x32_bf16 v[32:35], v[116:119], v[86:89], v[32:35]
	v_mfma_f32_16x16x32_bf16 v[28:31], v[104:107], v[90:93], v[28:31]
	v_mfma_f32_16x16x32_bf16 v[24:27], v[108:111], v[90:93], v[24:27]
	v_mfma_f32_16x16x32_bf16 v[20:23], v[112:115], v[90:93], v[20:23]
	v_mfma_f32_16x16x32_bf16 v[16:19], v[116:119], v[90:93], v[16:19]
	v_mfma_f32_16x16x32_bf16 v[12:15], v[104:107], v[100:103], v[12:15]
	v_mfma_f32_16x16x32_bf16 v[8:11], v[108:111], v[100:103], v[8:11]
	v_mfma_f32_16x16x32_bf16 v[4:7], v[112:115], v[100:103], v[4:7]
	v_mfma_f32_16x16x32_bf16 v[0:3], v[116:119], v[100:103], v[0:3]
	s_setprio 0
	s_setprio 1
	s_waitcnt lgkmcnt(0)
	v_mfma_f32_16x16x32_bf16 v[60:63], v[226:229], v[210:213], v[60:63]
	v_mfma_f32_16x16x32_bf16 v[56:59], v[230:233], v[210:213], v[56:59]
	v_mfma_f32_16x16x32_bf16 v[52:55], v[234:237], v[210:213], v[52:55]
	v_mfma_f32_16x16x32_bf16 v[48:51], v[238:241], v[210:213], v[48:51]
	v_mfma_f32_16x16x32_bf16 v[44:47], v[226:229], v[214:217], v[44:47]
	v_mfma_f32_16x16x32_bf16 v[40:43], v[230:233], v[214:217], v[40:43]
	v_mfma_f32_16x16x32_bf16 v[36:39], v[234:237], v[214:217], v[36:39]
	v_mfma_f32_16x16x32_bf16 v[32:35], v[238:241], v[214:217], v[32:35]
	v_mfma_f32_16x16x32_bf16 v[28:31], v[226:229], v[218:221], v[28:31]
	v_mfma_f32_16x16x32_bf16 v[24:27], v[230:233], v[218:221], v[24:27]
	v_mfma_f32_16x16x32_bf16 v[20:23], v[234:237], v[218:221], v[20:23]
	v_mfma_f32_16x16x32_bf16 v[16:19], v[238:241], v[218:221], v[16:19]
	v_mfma_f32_16x16x32_bf16 v[12:15], v[226:229], v[222:225], v[12:15]
	v_mfma_f32_16x16x32_bf16 v[8:11], v[230:233], v[222:225], v[8:11]
	v_mfma_f32_16x16x32_bf16 v[4:7], v[234:237], v[222:225], v[4:7]
	v_mfma_f32_16x16x32_bf16 v[0:3], v[238:241], v[222:225], v[0:3]
	s_setprio 0
	s_waitcnt vmcnt(0)
	s_add_u32 s6, s6, 0x80
	s_addc_u32 s7, s7, 0
	s_cmpk_lg_i32 s6, 0x780
	s_mov_b32 s1, s5
	s_waitcnt vmcnt(0)
	s_barrier
	s_cbranch_scc1 .LBB0_569
	v_add_u32_e32 v81, v79, v77
	ds_read_b128 v[70:73], v81 offset:55296
	ds_read_b128 v[82:85], v81 offset:53248
	ds_read_b128 v[86:89], v81 offset:51200
	ds_read_b128 v[90:93], v81 offset:49152
	v_add_u32_e32 v81, v79, v76
	ds_read_b128 v[100:103], v81 offset:38912
	ds_read_b128 v[104:107], v81 offset:36864
	ds_read_b128 v[108:111], v81 offset:34816
	ds_read_b128 v[112:115], v81 offset:32768
	s_setprio 1
	s_waitcnt lgkmcnt(0)
	v_mfma_f32_16x16x32_bf16 v[60:63], v[90:93], v[112:115], v[60:63]
	v_mfma_f32_16x16x32_bf16 v[56:59], v[86:89], v[112:115], v[56:59]
	v_mfma_f32_16x16x32_bf16 v[52:55], v[82:85], v[112:115], v[52:55]
	v_mfma_f32_16x16x32_bf16 v[48:51], v[70:73], v[112:115], v[48:51]
	v_mfma_f32_16x16x32_bf16 v[44:47], v[90:93], v[108:111], v[44:47]
	v_mfma_f32_16x16x32_bf16 v[40:43], v[86:89], v[108:111], v[40:43]
	v_mfma_f32_16x16x32_bf16 v[36:39], v[82:85], v[108:111], v[36:39]
	v_mfma_f32_16x16x32_bf16 v[32:35], v[70:73], v[108:111], v[32:35]
	v_mfma_f32_16x16x32_bf16 v[28:31], v[90:93], v[104:107], v[28:31]
	v_mfma_f32_16x16x32_bf16 v[24:27], v[86:89], v[104:107], v[24:27]
	v_mfma_f32_16x16x32_bf16 v[20:23], v[82:85], v[104:107], v[20:23]
	v_mfma_f32_16x16x32_bf16 v[16:19], v[70:73], v[104:107], v[16:19]
	v_mfma_f32_16x16x32_bf16 v[12:15], v[90:93], v[100:103], v[12:15]
	v_mfma_f32_16x16x32_bf16 v[8:11], v[86:89], v[100:103], v[8:11]
	v_mfma_f32_16x16x32_bf16 v[4:7], v[82:85], v[100:103], v[4:7]
	v_mfma_f32_16x16x32_bf16 v[0:3], v[70:73], v[100:103], v[0:3]
	s_setprio 0
	v_add_u32_e32 v81, v80, v76
	ds_read_b128 v[70:73], v81 offset:32768
	ds_read_b128 v[82:85], v81 offset:34816
	ds_read_b128 v[86:89], v81 offset:36864
	ds_read_b128 v[90:93], v81 offset:38912
	v_add_u32_e32 v81, v80, v77
	ds_read_b128 v[100:103], v81 offset:49152
	ds_read_b128 v[104:107], v81 offset:51200
	ds_read_b128 v[108:111], v81 offset:53248
	ds_read_b128 v[112:115], v81 offset:55296
	s_setprio 1
	s_waitcnt lgkmcnt(3)
	v_mfma_f32_16x16x32_bf16 v[60:63], v[100:103], v[70:73], v[60:63]
	s_waitcnt lgkmcnt(2)
	v_mfma_f32_16x16x32_bf16 v[56:59], v[104:107], v[70:73], v[56:59]
	s_waitcnt lgkmcnt(1)
	v_mfma_f32_16x16x32_bf16 v[52:55], v[108:111], v[70:73], v[52:55]
	s_waitcnt lgkmcnt(0)
	v_mfma_f32_16x16x32_bf16 v[48:51], v[112:115], v[70:73], v[48:51]
	v_mfma_f32_16x16x32_bf16 v[44:47], v[100:103], v[82:85], v[44:47]
	v_mfma_f32_16x16x32_bf16 v[40:43], v[104:107], v[82:85], v[40:43]
	v_mfma_f32_16x16x32_bf16 v[36:39], v[108:111], v[82:85], v[36:39]
	v_mfma_f32_16x16x32_bf16 v[32:35], v[112:115], v[82:85], v[32:35]
	v_mfma_f32_16x16x32_bf16 v[28:31], v[100:103], v[86:89], v[28:31]
	v_mfma_f32_16x16x32_bf16 v[24:27], v[104:107], v[86:89], v[24:27]
	v_mfma_f32_16x16x32_bf16 v[20:23], v[108:111], v[86:89], v[20:23]
	v_mfma_f32_16x16x32_bf16 v[16:19], v[112:115], v[86:89], v[16:19]
	v_mfma_f32_16x16x32_bf16 v[12:15], v[100:103], v[90:93], v[12:15]
	v_mfma_f32_16x16x32_bf16 v[8:11], v[104:107], v[90:93], v[8:11]
	v_mfma_f32_16x16x32_bf16 v[4:7], v[108:111], v[90:93], v[4:7]
	v_mfma_f32_16x16x32_bf16 v[0:3], v[112:115], v[90:93], v[0:3]
	s_setprio 0
	v_mov_b32_e32 v70, v97
	s_waitcnt vmcnt(0)
	s_barrier
	s_lshl_b32 s0, s0, 7
	v_add_u32_e32 v70, v70, v176
	v_and_b32_e32 v71, 64, v70
	v_ashrrev_i32_e32 v72, 1, v70
	v_lshrrev_b32_e32 v73, 2, v70
	v_and_or_b32 v70, v70, 15, s0
	s_lshl_b32 s0, s4, 7
	s_ashr_i32 s1, s0, 31
	s_lshl_b64 s[0:1], s[0:1], 1
	s_mov_b32 s6, 0
	v_and_b32_e32 v72, 0xffffffc0, v72
	s_add_u32 s0, s2, s0
	v_and_or_b32 v81, v73, 12, v71
	v_add_u32_e32 v82, v70, v72
	s_addc_u32 s1, s8, s1
	v_lshlrev_b32_e32 v96, 1, v81
	v_and_b32_sdwa v81, v62, v154 dst_sel:DWORD dst_unused:UNUSED_PAD src0_sel:WORD_1 src1_sel:DWORD
	v_and_b32_sdwa v83, v60, v154 dst_sel:DWORD dst_unused:UNUSED_PAD src0_sel:WORD_1 src1_sel:DWORD
	v_add3_u32 v60, v60, v83, s33
	v_add3_u32 v62, v62, v81, s33
	v_and_b32_sdwa v81, v63, v154 dst_sel:DWORD dst_unused:UNUSED_PAD src0_sel:WORD_1 src1_sel:DWORD
	v_and_b32_sdwa v83, v61, v154 dst_sel:DWORD dst_unused:UNUSED_PAD src0_sel:WORD_1 src1_sel:DWORD
	v_mov_b64_e32 v[70:71], s[0:1]
	s_movk_i32 s4, 0x3200
	v_add3_u32 v63, v63, v81, s33
	v_add3_u32 v61, v61, v83, s33
	v_mad_i64_i32 v[72:73], s[0:1], v82, s4, v[70:71]
	v_and_b32_e32 v63, 0xffff0000, v63
	v_and_b32_e32 v81, 0xffff0000, v61
	v_lshl_add_u64 v[72:73], v[72:73], 0, v[96:97]
	v_or_b32_sdwa v61, v63, v62 dst_sel:DWORD dst_unused:UNUSED_PAD src0_sel:DWORD src1_sel:WORD_1
	v_or_b32_sdwa v60, v81, v60 dst_sel:DWORD dst_unused:UNUSED_PAD src0_sel:DWORD src1_sel:WORD_1
	global_store_dwordx2 v[72:73], v[60:61], off
	v_and_b32_sdwa v60, v58, v154 dst_sel:DWORD dst_unused:UNUSED_PAD src0_sel:WORD_1 src1_sel:DWORD
	v_and_b32_sdwa v61, v56, v154 dst_sel:DWORD dst_unused:UNUSED_PAD src0_sel:WORD_1 src1_sel:DWORD
	v_add3_u32 v56, v56, v61, s33
	v_add3_u32 v58, v58, v60, s33
	v_and_b32_sdwa v60, v59, v154 dst_sel:DWORD dst_unused:UNUSED_PAD src0_sel:WORD_1 src1_sel:DWORD
	v_and_b32_sdwa v61, v57, v154 dst_sel:DWORD dst_unused:UNUSED_PAD src0_sel:WORD_1 src1_sel:DWORD
	v_add3_u32 v59, v59, v60, s33
	v_add3_u32 v57, v57, v61, s33
	v_and_b32_e32 v59, 0xffff0000, v59
	v_and_b32_e32 v60, 0xffff0000, v57
	v_or_b32_sdwa v57, v59, v58 dst_sel:DWORD dst_unused:UNUSED_PAD src0_sel:DWORD src1_sel:WORD_1
	v_or_b32_sdwa v56, v60, v56 dst_sel:DWORD dst_unused:UNUSED_PAD src0_sel:DWORD src1_sel:WORD_1
	global_store_dwordx2 v[72:73], v[56:57], off offset:32
	v_and_b32_sdwa v56, v54, v154 dst_sel:DWORD dst_unused:UNUSED_PAD src0_sel:WORD_1 src1_sel:DWORD
	v_and_b32_sdwa v57, v52, v154 dst_sel:DWORD dst_unused:UNUSED_PAD src0_sel:WORD_1 src1_sel:DWORD
	v_add3_u32 v52, v52, v57, s33
	v_add3_u32 v54, v54, v56, s33
	v_and_b32_sdwa v56, v55, v154 dst_sel:DWORD dst_unused:UNUSED_PAD src0_sel:WORD_1 src1_sel:DWORD
	v_and_b32_sdwa v57, v53, v154 dst_sel:DWORD dst_unused:UNUSED_PAD src0_sel:WORD_1 src1_sel:DWORD
	v_add3_u32 v55, v55, v56, s33
	v_add3_u32 v53, v53, v57, s33
	v_and_b32_e32 v55, 0xffff0000, v55
	v_and_b32_e32 v56, 0xffff0000, v53
	v_or_b32_sdwa v53, v55, v54 dst_sel:DWORD dst_unused:UNUSED_PAD src0_sel:DWORD src1_sel:WORD_1
	v_or_b32_sdwa v52, v56, v52 dst_sel:DWORD dst_unused:UNUSED_PAD src0_sel:DWORD src1_sel:WORD_1
	global_store_dwordx2 v[72:73], v[52:53], off offset:64
	v_and_b32_sdwa v52, v50, v154 dst_sel:DWORD dst_unused:UNUSED_PAD src0_sel:WORD_1 src1_sel:DWORD
	v_and_b32_sdwa v53, v48, v154 dst_sel:DWORD dst_unused:UNUSED_PAD src0_sel:WORD_1 src1_sel:DWORD
	v_add3_u32 v48, v48, v53, s33
	v_add3_u32 v50, v50, v52, s33
	v_and_b32_sdwa v52, v51, v154 dst_sel:DWORD dst_unused:UNUSED_PAD src0_sel:WORD_1 src1_sel:DWORD
	v_and_b32_sdwa v53, v49, v154 dst_sel:DWORD dst_unused:UNUSED_PAD src0_sel:WORD_1 src1_sel:DWORD
	v_add3_u32 v51, v51, v52, s33
	v_add3_u32 v49, v49, v53, s33
	v_and_b32_e32 v51, 0xffff0000, v51
	v_and_b32_e32 v52, 0xffff0000, v49
	v_or_b32_sdwa v49, v51, v50 dst_sel:DWORD dst_unused:UNUSED_PAD src0_sel:DWORD src1_sel:WORD_1
	v_or_b32_sdwa v48, v52, v48 dst_sel:DWORD dst_unused:UNUSED_PAD src0_sel:DWORD src1_sel:WORD_1
	global_store_dwordx2 v[72:73], v[48:49], off offset:96
	v_and_b32_sdwa v50, v46, v154 dst_sel:DWORD dst_unused:UNUSED_PAD src0_sel:WORD_1 src1_sel:DWORD
	v_and_b32_sdwa v51, v44, v154 dst_sel:DWORD dst_unused:UNUSED_PAD src0_sel:WORD_1 src1_sel:DWORD
	v_add3_u32 v44, v44, v51, s33
	v_add3_u32 v46, v46, v50, s33
	v_and_b32_sdwa v50, v47, v154 dst_sel:DWORD dst_unused:UNUSED_PAD src0_sel:WORD_1 src1_sel:DWORD
	v_and_b32_sdwa v51, v45, v154 dst_sel:DWORD dst_unused:UNUSED_PAD src0_sel:WORD_1 src1_sel:DWORD
	v_or_b32_e32 v48, 16, v82
	v_add3_u32 v47, v47, v50, s33
	v_add3_u32 v45, v45, v51, s33
	v_mad_i64_i32 v[48:49], s[0:1], v48, s4, v[70:71]
	v_and_b32_e32 v47, 0xffff0000, v47
	v_and_b32_e32 v50, 0xffff0000, v45
	v_lshl_add_u64 v[48:49], v[48:49], 0, v[96:97]
	v_or_b32_sdwa v45, v47, v46 dst_sel:DWORD dst_unused:UNUSED_PAD src0_sel:DWORD src1_sel:WORD_1
	v_or_b32_sdwa v44, v50, v44 dst_sel:DWORD dst_unused:UNUSED_PAD src0_sel:DWORD src1_sel:WORD_1
	global_store_dwordx2 v[48:49], v[44:45], off
	v_and_b32_sdwa v44, v42, v154 dst_sel:DWORD dst_unused:UNUSED_PAD src0_sel:WORD_1 src1_sel:DWORD
	v_and_b32_sdwa v45, v40, v154 dst_sel:DWORD dst_unused:UNUSED_PAD src0_sel:WORD_1 src1_sel:DWORD
	v_add3_u32 v40, v40, v45, s33
	v_add3_u32 v42, v42, v44, s33
	v_and_b32_sdwa v44, v43, v154 dst_sel:DWORD dst_unused:UNUSED_PAD src0_sel:WORD_1 src1_sel:DWORD
	v_and_b32_sdwa v45, v41, v154 dst_sel:DWORD dst_unused:UNUSED_PAD src0_sel:WORD_1 src1_sel:DWORD
	v_add3_u32 v43, v43, v44, s33
	v_add3_u32 v41, v41, v45, s33
	v_and_b32_e32 v43, 0xffff0000, v43
	v_and_b32_e32 v44, 0xffff0000, v41
	v_or_b32_sdwa v41, v43, v42 dst_sel:DWORD dst_unused:UNUSED_PAD src0_sel:DWORD src1_sel:WORD_1
	v_or_b32_sdwa v40, v44, v40 dst_sel:DWORD dst_unused:UNUSED_PAD src0_sel:DWORD src1_sel:WORD_1
	global_store_dwordx2 v[48:49], v[40:41], off offset:32
	v_and_b32_sdwa v40, v38, v154 dst_sel:DWORD dst_unused:UNUSED_PAD src0_sel:WORD_1 src1_sel:DWORD
	v_and_b32_sdwa v41, v36, v154 dst_sel:DWORD dst_unused:UNUSED_PAD src0_sel:WORD_1 src1_sel:DWORD
	v_add3_u32 v36, v36, v41, s33
	v_add3_u32 v38, v38, v40, s33
	v_and_b32_sdwa v40, v39, v154 dst_sel:DWORD dst_unused:UNUSED_PAD src0_sel:WORD_1 src1_sel:DWORD
	v_and_b32_sdwa v41, v37, v154 dst_sel:DWORD dst_unused:UNUSED_PAD src0_sel:WORD_1 src1_sel:DWORD
	v_add3_u32 v39, v39, v40, s33
	v_add3_u32 v37, v37, v41, s33
	v_and_b32_e32 v39, 0xffff0000, v39
	v_and_b32_e32 v40, 0xffff0000, v37
	v_or_b32_sdwa v37, v39, v38 dst_sel:DWORD dst_unused:UNUSED_PAD src0_sel:DWORD src1_sel:WORD_1
	v_or_b32_sdwa v36, v40, v36 dst_sel:DWORD dst_unused:UNUSED_PAD src0_sel:DWORD src1_sel:WORD_1
	global_store_dwordx2 v[48:49], v[36:37], off offset:64
	v_and_b32_sdwa v36, v34, v154 dst_sel:DWORD dst_unused:UNUSED_PAD src0_sel:WORD_1 src1_sel:DWORD
	v_and_b32_sdwa v37, v32, v154 dst_sel:DWORD dst_unused:UNUSED_PAD src0_sel:WORD_1 src1_sel:DWORD
	v_add3_u32 v32, v32, v37, s33
	v_add3_u32 v34, v34, v36, s33
	v_and_b32_sdwa v36, v35, v154 dst_sel:DWORD dst_unused:UNUSED_PAD src0_sel:WORD_1 src1_sel:DWORD
	v_and_b32_sdwa v37, v33, v154 dst_sel:DWORD dst_unused:UNUSED_PAD src0_sel:WORD_1 src1_sel:DWORD
	v_add3_u32 v35, v35, v36, s33
	v_add3_u32 v33, v33, v37, s33
	v_and_b32_e32 v35, 0xffff0000, v35
	v_and_b32_e32 v36, 0xffff0000, v33
	v_or_b32_sdwa v33, v35, v34 dst_sel:DWORD dst_unused:UNUSED_PAD src0_sel:DWORD src1_sel:WORD_1
	v_or_b32_sdwa v32, v36, v32 dst_sel:DWORD dst_unused:UNUSED_PAD src0_sel:DWORD src1_sel:WORD_1
	global_store_dwordx2 v[48:49], v[32:33], off offset:96
	v_and_b32_sdwa v34, v30, v154 dst_sel:DWORD dst_unused:UNUSED_PAD src0_sel:WORD_1 src1_sel:DWORD
	v_and_b32_sdwa v35, v28, v154 dst_sel:DWORD dst_unused:UNUSED_PAD src0_sel:WORD_1 src1_sel:DWORD
	v_add3_u32 v28, v28, v35, s33
	v_add3_u32 v30, v30, v34, s33
	v_and_b32_sdwa v34, v31, v154 dst_sel:DWORD dst_unused:UNUSED_PAD src0_sel:WORD_1 src1_sel:DWORD
	v_and_b32_sdwa v35, v29, v154 dst_sel:DWORD dst_unused:UNUSED_PAD src0_sel:WORD_1 src1_sel:DWORD
	v_or_b32_e32 v32, 32, v82
	v_add3_u32 v31, v31, v34, s33
	v_add3_u32 v29, v29, v35, s33
	v_mad_i64_i32 v[32:33], s[0:1], v32, s4, v[70:71]
	v_and_b32_e32 v31, 0xffff0000, v31
	v_and_b32_e32 v34, 0xffff0000, v29
	v_lshl_add_u64 v[32:33], v[32:33], 0, v[96:97]
	v_or_b32_sdwa v29, v31, v30 dst_sel:DWORD dst_unused:UNUSED_PAD src0_sel:DWORD src1_sel:WORD_1
	v_or_b32_sdwa v28, v34, v28 dst_sel:DWORD dst_unused:UNUSED_PAD src0_sel:DWORD src1_sel:WORD_1
	global_store_dwordx2 v[32:33], v[28:29], off
	v_and_b32_sdwa v28, v26, v154 dst_sel:DWORD dst_unused:UNUSED_PAD src0_sel:WORD_1 src1_sel:DWORD
	v_and_b32_sdwa v29, v24, v154 dst_sel:DWORD dst_unused:UNUSED_PAD src0_sel:WORD_1 src1_sel:DWORD
	v_add3_u32 v24, v24, v29, s33
	v_add3_u32 v26, v26, v28, s33
	v_and_b32_sdwa v28, v27, v154 dst_sel:DWORD dst_unused:UNUSED_PAD src0_sel:WORD_1 src1_sel:DWORD
	v_and_b32_sdwa v29, v25, v154 dst_sel:DWORD dst_unused:UNUSED_PAD src0_sel:WORD_1 src1_sel:DWORD
	v_add3_u32 v27, v27, v28, s33
	v_add3_u32 v25, v25, v29, s33
	v_and_b32_e32 v27, 0xffff0000, v27
	v_and_b32_e32 v28, 0xffff0000, v25
	v_or_b32_sdwa v25, v27, v26 dst_sel:DWORD dst_unused:UNUSED_PAD src0_sel:DWORD src1_sel:WORD_1
	v_or_b32_sdwa v24, v28, v24 dst_sel:DWORD dst_unused:UNUSED_PAD src0_sel:DWORD src1_sel:WORD_1
	global_store_dwordx2 v[32:33], v[24:25], off offset:32
	v_and_b32_sdwa v24, v22, v154 dst_sel:DWORD dst_unused:UNUSED_PAD src0_sel:WORD_1 src1_sel:DWORD
	v_and_b32_sdwa v25, v20, v154 dst_sel:DWORD dst_unused:UNUSED_PAD src0_sel:WORD_1 src1_sel:DWORD
	v_add3_u32 v20, v20, v25, s33
	v_add3_u32 v22, v22, v24, s33
	v_and_b32_sdwa v24, v23, v154 dst_sel:DWORD dst_unused:UNUSED_PAD src0_sel:WORD_1 src1_sel:DWORD
	v_and_b32_sdwa v25, v21, v154 dst_sel:DWORD dst_unused:UNUSED_PAD src0_sel:WORD_1 src1_sel:DWORD
	v_add3_u32 v23, v23, v24, s33
	v_add3_u32 v21, v21, v25, s33
	v_and_b32_e32 v23, 0xffff0000, v23
	v_and_b32_e32 v24, 0xffff0000, v21
	v_or_b32_sdwa v21, v23, v22 dst_sel:DWORD dst_unused:UNUSED_PAD src0_sel:DWORD src1_sel:WORD_1
	v_or_b32_sdwa v20, v24, v20 dst_sel:DWORD dst_unused:UNUSED_PAD src0_sel:DWORD src1_sel:WORD_1
	global_store_dwordx2 v[32:33], v[20:21], off offset:64
	v_and_b32_sdwa v20, v18, v154 dst_sel:DWORD dst_unused:UNUSED_PAD src0_sel:WORD_1 src1_sel:DWORD
	v_and_b32_sdwa v21, v16, v154 dst_sel:DWORD dst_unused:UNUSED_PAD src0_sel:WORD_1 src1_sel:DWORD
	v_add3_u32 v16, v16, v21, s33
	v_add3_u32 v18, v18, v20, s33
	v_and_b32_sdwa v20, v19, v154 dst_sel:DWORD dst_unused:UNUSED_PAD src0_sel:WORD_1 src1_sel:DWORD
	v_and_b32_sdwa v21, v17, v154 dst_sel:DWORD dst_unused:UNUSED_PAD src0_sel:WORD_1 src1_sel:DWORD
	v_add3_u32 v19, v19, v20, s33
	v_add3_u32 v17, v17, v21, s33
	v_and_b32_e32 v19, 0xffff0000, v19
	v_and_b32_e32 v20, 0xffff0000, v17
	v_or_b32_sdwa v17, v19, v18 dst_sel:DWORD dst_unused:UNUSED_PAD src0_sel:DWORD src1_sel:WORD_1
	v_or_b32_sdwa v16, v20, v16 dst_sel:DWORD dst_unused:UNUSED_PAD src0_sel:DWORD src1_sel:WORD_1
	global_store_dwordx2 v[32:33], v[16:17], off offset:96
	v_and_b32_sdwa v18, v14, v154 dst_sel:DWORD dst_unused:UNUSED_PAD src0_sel:WORD_1 src1_sel:DWORD
	v_and_b32_sdwa v19, v12, v154 dst_sel:DWORD dst_unused:UNUSED_PAD src0_sel:WORD_1 src1_sel:DWORD
	v_add3_u32 v12, v12, v19, s33
	v_add3_u32 v14, v14, v18, s33
	v_and_b32_sdwa v18, v15, v154 dst_sel:DWORD dst_unused:UNUSED_PAD src0_sel:WORD_1 src1_sel:DWORD
	v_and_b32_sdwa v19, v13, v154 dst_sel:DWORD dst_unused:UNUSED_PAD src0_sel:WORD_1 src1_sel:DWORD
	v_or_b32_e32 v16, 48, v82
	v_add3_u32 v15, v15, v18, s33
	v_add3_u32 v13, v13, v19, s33
	v_mad_i64_i32 v[16:17], s[0:1], v16, s4, v[70:71]
	v_and_b32_e32 v15, 0xffff0000, v15
	v_and_b32_e32 v18, 0xffff0000, v13
	v_lshl_add_u64 v[16:17], v[16:17], 0, v[96:97]
	v_or_b32_sdwa v13, v15, v14 dst_sel:DWORD dst_unused:UNUSED_PAD src0_sel:DWORD src1_sel:WORD_1
	v_or_b32_sdwa v12, v18, v12 dst_sel:DWORD dst_unused:UNUSED_PAD src0_sel:DWORD src1_sel:WORD_1
	global_store_dwordx2 v[16:17], v[12:13], off
	v_and_b32_sdwa v12, v10, v154 dst_sel:DWORD dst_unused:UNUSED_PAD src0_sel:WORD_1 src1_sel:DWORD
	v_and_b32_sdwa v13, v8, v154 dst_sel:DWORD dst_unused:UNUSED_PAD src0_sel:WORD_1 src1_sel:DWORD
	v_add3_u32 v8, v8, v13, s33
	v_add3_u32 v10, v10, v12, s33
	v_and_b32_sdwa v12, v11, v154 dst_sel:DWORD dst_unused:UNUSED_PAD src0_sel:WORD_1 src1_sel:DWORD
	v_and_b32_sdwa v13, v9, v154 dst_sel:DWORD dst_unused:UNUSED_PAD src0_sel:WORD_1 src1_sel:DWORD
	v_add3_u32 v11, v11, v12, s33
	v_add3_u32 v9, v9, v13, s33
	v_and_b32_e32 v11, 0xffff0000, v11
	v_and_b32_e32 v12, 0xffff0000, v9
	v_or_b32_sdwa v9, v11, v10 dst_sel:DWORD dst_unused:UNUSED_PAD src0_sel:DWORD src1_sel:WORD_1
	v_or_b32_sdwa v8, v12, v8 dst_sel:DWORD dst_unused:UNUSED_PAD src0_sel:DWORD src1_sel:WORD_1
	global_store_dwordx2 v[16:17], v[8:9], off offset:32
	v_and_b32_sdwa v8, v6, v154 dst_sel:DWORD dst_unused:UNUSED_PAD src0_sel:WORD_1 src1_sel:DWORD
	v_and_b32_sdwa v9, v4, v154 dst_sel:DWORD dst_unused:UNUSED_PAD src0_sel:WORD_1 src1_sel:DWORD
	v_add3_u32 v4, v4, v9, s33
	v_add3_u32 v6, v6, v8, s33
	v_and_b32_sdwa v8, v7, v154 dst_sel:DWORD dst_unused:UNUSED_PAD src0_sel:WORD_1 src1_sel:DWORD
	v_and_b32_sdwa v9, v5, v154 dst_sel:DWORD dst_unused:UNUSED_PAD src0_sel:WORD_1 src1_sel:DWORD
	v_add3_u32 v7, v7, v8, s33
	v_add3_u32 v5, v5, v9, s33
	v_and_b32_e32 v7, 0xffff0000, v7
	v_and_b32_e32 v8, 0xffff0000, v5
	v_or_b32_sdwa v5, v7, v6 dst_sel:DWORD dst_unused:UNUSED_PAD src0_sel:DWORD src1_sel:WORD_1
	v_or_b32_sdwa v4, v8, v4 dst_sel:DWORD dst_unused:UNUSED_PAD src0_sel:DWORD src1_sel:WORD_1
	global_store_dwordx2 v[16:17], v[4:5], off offset:64
	v_and_b32_sdwa v4, v2, v154 dst_sel:DWORD dst_unused:UNUSED_PAD src0_sel:WORD_1 src1_sel:DWORD
	v_and_b32_sdwa v5, v0, v154 dst_sel:DWORD dst_unused:UNUSED_PAD src0_sel:WORD_1 src1_sel:DWORD
	v_add3_u32 v0, v0, v5, s33
	v_add3_u32 v2, v2, v4, s33
	v_and_b32_sdwa v4, v3, v154 dst_sel:DWORD dst_unused:UNUSED_PAD src0_sel:WORD_1 src1_sel:DWORD
	v_and_b32_sdwa v5, v1, v154 dst_sel:DWORD dst_unused:UNUSED_PAD src0_sel:WORD_1 src1_sel:DWORD
	v_add3_u32 v3, v3, v4, s33
	v_add3_u32 v1, v1, v5, s33
	v_and_b32_e32 v3, 0xffff0000, v3
	v_and_b32_e32 v4, 0xffff0000, v1
	v_or_b32_sdwa v1, v3, v2 dst_sel:DWORD dst_unused:UNUSED_PAD src0_sel:DWORD src1_sel:WORD_1
	v_or_b32_sdwa v0, v4, v0 dst_sel:DWORD dst_unused:UNUSED_PAD src0_sel:DWORD src1_sel:WORD_1
	global_store_dwordx2 v[16:17], v[0:1], off offset:96
